# memory-attention tile loop: tile j+2 LDS-DMA issue also moved from the tile head to mid-tile
# baseline (speedup 1.0000x reference)
;     ...
;         if (t + 2 < NT) AT_ISSUE(sn2);
;         const bool active = !CAUSAL || (64 * t <= qmin + 31);
;         if (active) {
;             const LAS char* kb_ = lds + sc * SLOT + r * KP + 16 * h; const LAS char* vb_ = lds + sc * SLOT + KBUF + (4 * h + q4) * VP + blk * 32 + p4 * 8;
;             f32x16 s0, s1;
;             bf16x8 fa[HB], fb[HB];
;             const unsigned va_ = (unsigned)(size_t)vb_;
;             s16x4 la[4], ha[4];
;             float m0 = 0.f, ps = 0.f; bf16x8 pf[4];
;             SB(); LDH(fa, 0, 0); SB();
; #pragma unroll
;             for (int bb = 0; bb < 2 * NBH; ++bb) {
;                 const int nb = bb + 1;
;                 if (nb < 2 * NBH) { if (nb & 1) LDH(fb, nb / NBH, nb % NBH); else LDH(fa, nb / NBH, nb % NBH); }
;                 SB();
;                 if (bb < NBH) { if (bb & 1) MMH(s0, fb, bb % NBH); else MMH(s0, fa, bb % NBH); }
;                 else          { if (bb & 1) MMH(s1, fb, bb % NBH); else MMH(s1, fa, bb % NBH); }
;                 if (bb == NBH) {
;                     if (CAUSAL && (64 * t + 31 > qmin)) {
; #pragma unroll
;                         for (int i = 0; i < 16; ++i) { const int kv = 64 * t + crow(i, h); if (kv > qpos) s0[i] = -INFINITY; } }
;                     float m0b = fmaxf(fmaxf(s0[3], s0[4]), s0[5]); m0 = fmaxf(fmaxf(s0[0], s0[1]), s0[2]);
; #pragma unroll
;                     for (int i = 6; i < 15; i += 3) { m0 = fmaxf(fmaxf(m0, s0[i]), s0[i + 1]); m0b = fmaxf(m0b, s0[i + 2]); }
;                     m0 = fmaxf(fmaxf(m0, m0b), s0[15]);
; #pragma unroll
;                     for (int i = 0; i < 16; ++i) { s0[i] = __builtin_amdgcn_exp2f(s0[i]); ps += s0[i]; }
;                     pf[0] = pack8(s0, 0); pf[1] = pack8(s0, 8); }
;                 SB(); }
;             LDV(la, ha, 0); SB(); LGKM(0); SB();
;             MMV(la, ha, 0); SB(); LDV(la, ha, 1); LGKM(0); SB(); MMV(la, ha, 1); SB(); LDV(la, ha, 2); SB();
;             if (CAUSAL && (64 * t + 63 > qmin)) {
; #pragma unroll
;                 for (int i = 0; i < 16; ++i) { const int kv = 64 * t + 32 + crow(i, h); if (kv > qpos) s1[i] = -INFINITY; } }
;             float m1 = fmaxf(fmaxf(s1[0], s1[1]), s1[2]), m1b = fmaxf(fmaxf(s1[3], s1[4]), s1[5]);
; #pragma unroll
;             for (int i = 6; i < 15; i += 3) { m1 = fmaxf(fmaxf(m1, s1[i]), s1[i + 1]); m1b = fmaxf(m1b, s1[i + 2]); }
.LBB0_602:
	s_cmp_gt_u32 s15, 1
	s_cselect_b64 s[6:7], -1, 0
	s_mov_b32 s17, s10
	s_mul_i32 s32, s8, 0x9400
.LBB0_604:
	s_mul_i32 s8, s17, 0x9400
	s_add_i32 s8, s8, 0
	v_add3_u32 v164, s8, v1, v162
	v_add3_u32 v98, s8, v163, v166
	ds_read_b128 v[82:85], v164
	ds_read_b128 v[86:89], v164 offset:32
	ds_read_b128 v[90:93], v164 offset:64
	ds_read_b128 v[94:97], v164 offset:96
	s_movk_i32 s8, 0x4400
	v_add3_u32 v169, v98, v167, s8
	ds_read_b128 v[146:149], v164 offset:128
	ds_read_b128 v[170:173], v164 offset:160
	ds_read_b128 v[174:177], v164 offset:192
	ds_read_b128 v[180:183], v164 offset:224
	s_waitcnt lgkmcnt(0)
	v_mfma_f32_32x32x16_bf16 v[98:113], v[82:85], v[114:117], v[66:81]
	v_mfma_f32_32x32x16_bf16 v[98:113], v[86:89], v[118:121], v[98:113]
	v_mfma_f32_32x32x16_bf16 v[98:113], v[90:93], v[122:125], v[98:113]
	v_mfma_f32_32x32x16_bf16 v[98:113], v[94:97], v[126:129], v[98:113]
	ds_read_b128 v[184:187], v164 offset:8704
	ds_read_b128 v[188:191], v164 offset:8736
	ds_read_b128 v[192:195], v164 offset:8768
	ds_read_b128 v[196:199], v164 offset:8800
	v_mfma_f32_32x32x16_bf16 v[98:113], v[146:149], v[130:133], v[98:113]
	v_mfma_f32_32x32x16_bf16 v[98:113], v[170:173], v[134:137], v[98:113]
	v_mfma_f32_32x32x16_bf16 v[98:113], v[174:177], v[138:141], v[98:113]
	v_mfma_f32_32x32x16_bf16 v[98:113], v[180:183], v[142:145], v[98:113]
	ds_read_b128 v[146:149], v164 offset:8832
	ds_read_b128 v[170:173], v164 offset:8864
	ds_read_b128 v[174:177], v164 offset:8896
	ds_read_b128 v[180:183], v164 offset:8928
	s_nop 7
	v_max_f32_e32 v164, v102, v102
	v_max_f32_e32 v200, v101, v101
	s_waitcnt lgkmcnt(0)
	v_mfma_f32_32x32x16_bf16 v[82:97], v[184:187], v[114:117], v[66:81]
	v_max_f32_e32 v201, v98, v98
	v_exp_f32_e32 v98, v98
	v_max_f32_e32 v164, v200, v164
	v_max_f32_e32 v200, v99, v99
	v_exp_f32_e32 v99, v99
	v_exp_f32_e32 v186, v100
	v_max3_f32 v164, v164, v103, v106
	v_mfma_f32_32x32x16_bf16 v[82:97], v[188:191], v[118:121], v[82:97]
	v_exp_f32_e32 v101, v101
	v_max3_f32 v185, v164, v109, v112
	v_add_f32_e32 v164, 0, v98
	v_exp_f32_e32 v102, v102
	v_add_f32_e32 v164, v99, v164
	v_exp_f32_e32 v103, v103
	v_add_f32_e32 v164, v186, v164
	v_mfma_f32_32x32x16_bf16 v[82:97], v[192:195], v[122:125], v[82:97]
	v_exp_f32_e32 v187, v104
	v_add_f32_e32 v164, v101, v164
	v_exp_f32_e32 v188, v105
	v_add_f32_e32 v164, v102, v164
	v_exp_f32_e32 v106, v106
	v_add_f32_e32 v164, v103, v164
	v_exp_f32_e32 v189, v107
	v_add_f32_e32 v164, v187, v164
	v_exp_f32_e32 v190, v108
	v_add_f32_e32 v164, v188, v164
	v_exp_f32_e32 v109, v109
	v_mfma_f32_32x32x16_bf16 v[82:97], v[196:199], v[126:129], v[82:97]
	v_add_f32_e32 v164, v106, v164
	v_exp_f32_e32 v191, v110
	v_add_f32_e32 v164, v189, v164
	v_exp_f32_e32 v192, v111
	v_add_f32_e32 v164, v190, v164
	v_exp_f32_e32 v112, v112
	v_max_f32_e32 v184, v201, v200
	v_add_f32_e32 v164, v109, v164
	v_exp_f32_e32 v193, v113
	v_add_f32_e32 v164, v191, v164
	v_max3_f32 v100, v184, v100, v104
	v_add_f32_e32 v164, v192, v164
	v_max3_f32 v100, v100, v105, v107
	v_add_f32_e32 v164, v112, v164
	v_max3_f32 v100, v100, v108, v110
	v_add_f32_e32 v164, v193, v164
	v_max3_f32 v110, v100, v111, v185
	v_cvt_pk_bf16_f32 v98, v98, v99
	v_cvt_pk_bf16_f32 v99, v186, v101
	v_cvt_pk_bf16_f32 v100, v102, v103
	v_cvt_pk_bf16_f32 v101, v187, v188
	v_cvt_pk_bf16_f32 v102, v106, v189
	v_cvt_pk_bf16_f32 v103, v190, v109
	v_cvt_pk_bf16_f32 v104, v191, v192
	v_cvt_pk_bf16_f32 v105, v112, v193
	v_mfma_f32_32x32x16_bf16 v[82:97], v[146:149], v[130:133], v[82:97]
	v_mfma_f32_32x32x16_bf16 v[82:97], v[170:173], v[134:137], v[82:97]
	v_mfma_f32_32x32x16_bf16 v[82:97], v[174:177], v[138:141], v[82:97]
	v_mfma_f32_32x32x16_bf16 v[82:97], v[180:183], v[142:145], v[82:97]
	ds_read_b64_tr_b16 v[106:107], v169 offset:0
	ds_read_b64_tr_b16 v[108:109], v169 offset:2560
	ds_read_b64_tr_b16 v[146:147], v169 offset:64
	ds_read_b64_tr_b16 v[148:149], v169 offset:2624
	ds_read_b64_tr_b16 v[170:171], v169 offset:128
	ds_read_b64_tr_b16 v[172:173], v169 offset:2688
	ds_read_b64_tr_b16 v[174:175], v169 offset:192
	ds_read_b64_tr_b16 v[176:177], v169 offset:2752
	s_waitcnt lgkmcnt(0)
	s_nop 0
	v_mfma_f32_32x32x16_bf16 v[50:65], v[106:109], v[98:101], v[50:65]
	v_mfma_f32_32x32x16_bf16 v[34:49], v[146:149], v[98:101], v[34:49]
	v_mfma_f32_32x32x16_bf16 v[18:33], v[170:173], v[98:101], v[18:33]
	v_mfma_f32_32x32x16_bf16 v[2:17], v[174:177], v[98:101], v[2:17]
	ds_read_b64_tr_b16 v[98:99], v169 offset:5120
	ds_read_b64_tr_b16 v[100:101], v169 offset:7680
	ds_read_b64_tr_b16 v[106:107], v169 offset:5184
	ds_read_b64_tr_b16 v[108:109], v169 offset:7744
	ds_read_b64_tr_b16 v[146:147], v169 offset:5248
	ds_read_b64_tr_b16 v[148:149], v169 offset:7808
	ds_read_b64_tr_b16 v[170:171], v169 offset:5312
	ds_read_b64_tr_b16 v[172:173], v169 offset:7872
	s_waitcnt lgkmcnt(0)
	s_nop 0
	v_mfma_f32_32x32x16_bf16 v[50:65], v[98:101], v[102:105], v[50:65]
	v_mfma_f32_32x32x16_bf16 v[34:49], v[106:109], v[102:105], v[34:49]
	v_mfma_f32_32x32x16_bf16 v[18:33], v[146:149], v[102:105], v[18:33]
	v_mfma_f32_32x32x16_bf16 v[2:17], v[170:173], v[102:105], v[2:17]
	ds_read_b64_tr_b16 v[146:147], v169 offset:10240
	ds_read_b64_tr_b16 v[148:149], v169 offset:12800
	ds_read_b64_tr_b16 v[106:107], v169 offset:10304
	ds_read_b64_tr_b16 v[108:109], v169 offset:12864
	ds_read_b64_tr_b16 v[102:103], v169 offset:10368
	ds_read_b64_tr_b16 v[104:105], v169 offset:12928
	ds_read_b64_tr_b16 v[98:99], v169 offset:10432
	ds_read_b64_tr_b16 v[100:101], v169 offset:12992
	s_and_b64 vcc, exec, s[6:7]
	s_cbranch_vccnz .Lma_dma_done
	s_add_i32 m0, s32, s13
	s_nop 0
	global_load_lds_dwordx4 v[152:153], off
	s_add_i32 m0, s32, s12
	v_lshl_add_u64 v[152:153], v[152:153], 0, s[78:79]
	global_load_lds_dwordx4 v[154:155], off
	s_add_i32 m0, s32, s14
	v_lshl_add_u64 v[154:155], v[154:155], 0, s[78:79]
	global_load_lds_dwordx4 v[156:157], off
	s_add_i32 m0, s32, s16
	v_lshl_add_u64 v[156:157], v[156:157], 0, s[78:79]
	global_load_lds_dwordx4 v[158:159], off
	s_add_i32 m0, s32, s18
	v_lshl_add_u64 v[158:159], v[158:159], 0, s[78:79]
	global_load_lds_dwordx4 v[160:161], off
	v_lshl_add_u64 v[160:161], v[160:161], 0, s[78:79]
.Lma_dma_done:
	s_nop 1
	v_max3_f32 v111, v82, v83, v84
	v_max_f32_e32 v112, v86, v86
	v_max_f32_e32 v170, v85, v85
	v_max_f32_e32 v112, v170, v112
	v_max3_f32 v111, v111, v88, v89
	v_max3_f32 v112, v112, v87, v90
	v_max3_f32 v111, v111, v91, v92
	v_max3_f32 v111, v111, v94, v95
	v_max3_f32 v112, v112, v93, v96
	v_max3_f32 v111, v111, v112, v97
	v_max3_f32 v110, v110, v113, v111
	v_mov_b32_e32 v111, v110
	s_nop 1
	v_permlane32_swap_b32_e32 v110, v111
	v_max_f32_e32 v111, v111, v111
	v_max_f32_e32 v110, v110, v110
	s_cmp_lg_u32 s15, 0
	v_max_f32_e32 v111, v110, v111
	s_cbranch_scc0 .LBB0_618
	s_mov_b32 s8, 0x41000000
	v_cmp_lt_f32_e32 vcc, s8, v111
	s_mov_b64 s[10:11], 0
	s_mov_b64 s[8:9], 0
	s_cbranch_vccz .LBB0_607
	v_max_f32_e32 v110, v111, v111
	v_max_f32_e32 v110, 0, v110
	s_mov_b64 s[8:9], -1
